# global barrier: XCC leaders add to the cross-XCC counter without return and poll that counter (generation word and one hop removed)
# speedup vs baseline: 1.0090x; 1.0080x over previous
; DI void grid_barrier(unsigned* bar, unsigned gen) {
;   asm volatile("s_waitcnt vmcnt(0)" ::: "memory");
;   __syncthreads();
;   if (threadIdx.x == 0) {
;     __builtin_amdgcn_fence(__ATOMIC_RELEASE, "agent");
;     const unsigned grp = blockIdx.x & 15u;
;     const unsigned nblk = (gridDim.x + 15u - grp) >> 4;
;     unsigned old = __hip_atomic_fetch_add(bar + 64 * (1 + grp), 1u, __ATOMIC_RELAXED, __HIP_MEMORY_SCOPE_AGENT);
;     if (old + 1u == nblk * gen) {
;       unsigned g = __hip_atomic_fetch_add(bar, 1u, __ATOMIC_RELAXED, __HIP_MEMORY_SCOPE_AGENT);
;       if (g + 1u == 16u * gen) {
;         for (int i = 0; i < 16; ++i) __hip_atomic_store(bar + 64 * (17 + i), gen, __ATOMIC_RELAXED, __HIP_MEMORY_SCOPE_AGENT);
;       }
;     }
;     while (__hip_atomic_load(bar + 64 * (17 + grp), __ATOMIC_RELAXED, __HIP_MEMORY_SCOPE_AGENT) < gen) __builtin_amdgcn_s_sleep(4);
;     __builtin_amdgcn_fence(__ATOMIC_ACQUIRE, "agent");
;   }
.Lmy_xb_glob:
	v_mov_b32_e32 v0, s17
	v_add_u32_e32 v0, 0x1400, v0
	global_atomic_add v3, v0, v2, s[12:13] sc0
	buffer_inv sc1
	s_waitcnt vmcnt(0)
	v_readfirstlane_b32 s18, v3
	s_add_i32 s18, s18, 1
	s_mul_i32 s19, s20, s15
	s_cmp_eq_u32 s18, s19
	s_cbranch_scc0 .Lmy_xb_follow
	buffer_wbl2 sc1
	s_waitcnt vmcnt(0)
	v_mov_b32_e32 v0, 0x3400
	global_atomic_add v0, v2, s[12:13]
	s_mul_i32 s19, s20, s16
.Lmy_xb_spin_top:
	global_load_dword v3, v0, s[12:13] sc1
	s_waitcnt vmcnt(0)
	v_readfirstlane_b32 s18, v3
	s_cmp_lt_u32 s18, s19
	s_cbranch_scc0 .Lmy_xb_lead_acq
	s_sleep 1
	s_branch .Lmy_xb_spin_top
